# v096 + first grid barrier: the 16 per-XCC census counter loads are issued together and waited once (they were 16 serial memory round trips)
# speedup vs baseline: 1.0014x; 1.0014x over previous
.LBB0_93:
	global_load_dword v3, v195, s[94:95] sc1
	global_load_dword v2, v195, s[60:61] sc1
	s_mov_b64 s[8:9], -1
	v_readlane_b32 s6, v253, 8
	v_readlane_b32 s7, v253, 9
	s_nop 4
	global_load_dword v4, v195, s[6:7] sc1
	v_readlane_b32 s6, v253, 10
	v_readlane_b32 s7, v253, 11
	s_nop 4
	global_load_dword v5, v195, s[6:7] sc1
	v_readlane_b32 s6, v253, 12
	v_readlane_b32 s7, v253, 13
	s_nop 4
	global_load_dword v6, v195, s[6:7] sc1
	v_readlane_b32 s6, v253, 14
	v_readlane_b32 s7, v253, 15
	s_nop 4
	global_load_dword v7, v195, s[6:7] sc1
	v_readlane_b32 s6, v253, 16
	v_readlane_b32 s7, v253, 17
	s_nop 4
	global_load_dword v8, v195, s[6:7] sc1
	v_readlane_b32 s6, v253, 18
	v_readlane_b32 s7, v253, 19
	s_nop 4
	global_load_dword v9, v195, s[6:7] sc1
	v_readlane_b32 s6, v253, 20
	v_readlane_b32 s7, v253, 21
	s_nop 4
	global_load_dword v10, v195, s[6:7] sc1
	v_readlane_b32 s6, v253, 22
	v_readlane_b32 s7, v253, 23
	s_nop 4
	global_load_dword v11, v195, s[6:7] sc1
	v_readlane_b32 s6, v253, 24
	v_readlane_b32 s7, v253, 25
	s_nop 4
	global_load_dword v12, v195, s[6:7] sc1
	v_readlane_b32 s6, v253, 26
	v_readlane_b32 s7, v253, 27
	s_nop 4
	global_load_dword v13, v195, s[6:7] sc1
	v_readlane_b32 s6, v253, 28
	v_readlane_b32 s7, v253, 29
	s_nop 4
	global_load_dword v14, v195, s[6:7] sc1
	v_readlane_b32 s6, v253, 30
	v_readlane_b32 s7, v253, 31
	s_nop 4
	global_load_dword v15, v195, s[6:7] sc1
	v_readlane_b32 s6, v253, 32
	v_readlane_b32 s7, v253, 33
	s_nop 4
	global_load_dword v16, v195, s[6:7] sc1
	v_readlane_b32 s6, v253, 34
	v_readlane_b32 s7, v253, 35
	s_nop 4
	global_load_dword v17, v195, s[6:7] sc1
	s_mov_b64 s[6:7], -1
	s_waitcnt vmcnt(0)
	v_add_u32_e32 v18, v2, v3
	v_add_u32_e32 v18, v18, v4
	v_add_u32_e32 v18, v18, v5
	v_add_u32_e32 v18, v18, v6
	v_add_u32_e32 v18, v18, v7
	v_add_u32_e32 v18, v18, v8
	v_add_u32_e32 v18, v18, v9
	v_add_u32_e32 v18, v18, v10
	v_add_u32_e32 v18, v18, v11
	v_add_u32_e32 v18, v18, v12
	v_add_u32_e32 v18, v18, v13
	v_add_u32_e32 v18, v18, v14
	v_add_u32_e32 v18, v18, v15
	v_add_u32_e32 v18, v18, v16
	v_add_u32_e32 v18, v18, v17
	v_cmp_eq_u32_e32 vcc, s2, v18
	s_cbranch_vccnz .LBB0_92
	s_and_b32 s6, s12, 0xff
	s_cmp_eq_u32 s6, 0
	s_mov_b64 s[6:7], -1
	s_mov_b64 s[10:11], -1
	s_sleep 1
	s_cbranch_scc1 .LBB0_97
	s_and_b64 vcc, exec, s[10:11]
	s_cbranch_vccz .LBB0_92

.Lpb_next:
	s_add_i32 s65, s65, s3
	s_cmpk_lt_i32 s65, 0x440
	s_cbranch_scc1 .Lpb_loop
	s_branch .LBB0_178
	s_nop 0
	s_nop 0
	s_nop 0
	s_nop 0
	s_nop 0
	s_nop 0
	s_nop 0
	s_nop 0
	s_nop 0
	s_nop 0
	s_nop 0
	s_nop 0
	s_nop 0
	s_nop 0
	s_nop 0
	s_nop 0
	s_nop 0
	s_nop 0
	s_nop 0
	s_nop 0
	s_nop 0
	s_branch .LBB0_178
	s_nop 0
	s_nop 0
	s_nop 0
	s_nop 0
	s_nop 0
	s_nop 0
	s_nop 0
	s_nop 0
	s_nop 0
	s_nop 0
	s_nop 0
	s_nop 0
	s_nop 0
	s_nop 0
	s_nop 0
	s_nop 0
	s_nop 0
	s_nop 0
	s_nop 0
	s_nop 0
	s_nop 0
	s_nop 0
	s_nop 0
	s_nop 0
	s_nop 0
	s_nop 0
	s_nop 0
	s_nop 0
	s_nop 0
	s_nop 0
	s_nop 0
	s_nop 0
